# four overlap slots: 4096 layer-3 FFN weight items converted by the streamer WGs in the recurrence phase of every layer (the layer-3 slot added; these weights are first read after that phase)
# speedup vs baseline: 1.0054x; 1.0054x over previous
; #define LAS __attribute__((address_space(3)))
; __global__ void __launch_bounds__(NTHR, 2) mega(const Args a) {
;     extern __shared__ __attribute__((aligned(16))) unsigned char lds_raw[];
;     LAS unsigned char* lds = (LAS unsigned char*)lds_raw;
;     const int wg0 = blockIdx.x, nwg0 = gridDim.x, tid = threadIdx.x;
;     for (int u = tid; u < (LDS_BYTES - LDSCTL_OFF) / 4; u += NTHR) ((LAS unsigned*)(lds + LDSCTL_OFF))[u] = 0u;
;     __syncthreads();
;     if (tid == 0) { const unsigned long long* src = (const unsigned long long*)&a.p;
; #pragma unroll
;         for (int i = 0; i < 25; ++i) *(LAS unsigned long long*)(lds + LDS_P_OFF + 8 * i) = src[i]; }
;     __syncthreads();
_Z4mega4Args:
	v_mov_b32_e32 v250, 0
	s_mov_b32 s3, 0x1d300
	v_writelane_b32 v250, s3, 2
	s_mov_b32 s3, 0x1d2ff
	v_writelane_b32 v250, s3, 3
	s_add_u32 s4, s0, 0xd0
	s_addc_u32 s5, s1, 0
	s_movk_i32 s3, 0x200
	v_writelane_b32 v249, s4, 0
	v_cmp_gt_u32_e32 vcc, s3, v0
	s_nop 0
	v_writelane_b32 v249, s5, 1
	s_and_saveexec_b64 s[6:7], vcc
	v_lshl_add_u32 v1, v0, 2, 0
	v_add_u32_e32 v1, 0x23800, v1
	v_mov_b32_e32 v2, 0
	ds_write_b32 v1, v2
	s_or_b64 exec, exec, s[6:7]
	s_waitcnt lgkmcnt(0)
	s_barrier
	v_cmp_eq_u32_e64 s[4:5], 0, v0
	s_mov_b64 s[22:23], exec
	s_nop 0
	v_writelane_b32 v249, s4, 2
	s_nop 1
	v_writelane_b32 v249, s5, 3
	s_and_b64 s[4:5], s[22:23], s[4:5]
	s_mov_b64 exec, s[4:5]
	s_cbranch_execz .LBB0_4
	s_load_dwordx16 s[4:19], s[0:1], 0x0
	s_add_i32 s20, 0, 0x23900
	s_load_dwordx16 s[48:63], s[0:1], 0x40
	v_mov_b32_e32 v1, s20
	s_add_i32 s20, 0, 0x23970
	s_waitcnt lgkmcnt(0)
	v_mov_b32_e32 v2, s4
	v_mov_b32_e32 v3, s5
	v_mov_b32_e32 v4, s6
	v_mov_b32_e32 v5, s7
	s_add_i32 s4, 0, 0x23910
	ds_write_b128 v1, v[2:5]
	v_mov_b32_e32 v2, s8
	v_mov_b32_e32 v3, s9
	v_mov_b32_e32 v4, s10
	v_mov_b32_e32 v5, s11
	v_mov_b32_e32 v1, s4
	s_add_i32 s4, 0, 0x23920
	ds_write_b128 v1, v[2:5]
	v_mov_b32_e32 v2, s12
	v_mov_b32_e32 v3, s13
	v_mov_b32_e32 v4, s14
	v_mov_b32_e32 v5, s15
	v_mov_b32_e32 v1, s4
	s_add_i32 s4, 0, 0x23930
	ds_write_b128 v1, v[2:5]
	v_mov_b32_e32 v2, s16
	v_mov_b32_e32 v3, s17
	v_mov_b32_e32 v4, s18
	v_mov_b32_e32 v5, s19
	v_mov_b32_e32 v1, s4
	s_add_i32 s4, 0, 0x23940
	ds_write_b128 v1, v[2:5]
	v_mov_b32_e32 v2, s48
	v_mov_b32_e32 v3, s49
	v_mov_b32_e32 v4, s50
	v_mov_b32_e32 v5, s51
	v_mov_b32_e32 v1, s4
	s_add_i32 s4, 0, 0x23950
	ds_write_b128 v1, v[2:5]
	v_mov_b32_e32 v2, s52
	v_mov_b32_e32 v3, s53
	v_mov_b32_e32 v4, s54
	v_mov_b32_e32 v5, s55
	v_mov_b32_e32 v1, s4
	s_add_i32 s4, 0, 0x23960
	ds_write_b128 v1, v[2:5]
	v_mov_b32_e32 v1, s4
	s_load_dwordx16 s[4:19], s[0:1], 0x80
	v_mov_b32_e32 v2, s56
	v_mov_b32_e32 v3, s57
	v_mov_b32_e32 v4, s58
	v_mov_b32_e32 v5, s59
	ds_write_b128 v1, v[2:5]
	v_mov_b32_e32 v2, s60
	v_mov_b32_e32 v3, s61
	v_mov_b32_e32 v4, s62
	v_mov_b32_e32 v5, s63
	v_mov_b32_e32 v1, s20
	ds_write_b128 v1, v[2:5]
	s_waitcnt lgkmcnt(0)
	v_mov_b32_e32 v2, s4
	s_add_i32 s4, 0, 0x23980
	v_mov_b32_e32 v3, s5
	v_mov_b32_e32 v4, s6
	v_mov_b32_e32 v5, s7
	v_mov_b32_e32 v1, s4
	s_add_i32 s4, 0, 0x23990
	ds_write_b128 v1, v[2:5]
	v_mov_b32_e32 v2, s8
	v_mov_b32_e32 v3, s9
	v_mov_b32_e32 v4, s10
	v_mov_b32_e32 v5, s11
	v_mov_b32_e32 v1, s4
	s_add_i32 s4, 0, 0x239a0
	ds_write_b128 v1, v[2:5]
	v_mov_b32_e32 v1, s4
	s_load_dwordx2 s[4:5], s[0:1], 0xc0
	v_mov_b32_e32 v2, s12
	v_mov_b32_e32 v3, s13
	v_mov_b32_e32 v4, s14
	v_mov_b32_e32 v5, s15
	s_add_i32 s6, 0, 0x239b0
	ds_write_b128 v1, v[2:5]
	v_mov_b32_e32 v2, s16
	v_mov_b32_e32 v3, s17
	v_mov_b32_e32 v4, s18
	v_mov_b32_e32 v5, s19
	v_mov_b32_e32 v1, s6
	s_add_i32 s6, 0, 0x239c0
	ds_write_b128 v1, v[2:5]
	v_mov_b32_e32 v1, s6
	s_waitcnt lgkmcnt(0)
	v_mov_b64_e32 v[2:3], s[4:5]
	ds_write_b64 v1, v[2:3]

; #define LAS __attribute__((address_space(3)))
; __device__ __forceinline__ void phase_prologue(const P& p, unsigned char* ws, LAS unsigned char* lds, int wg, int nwg) {
;     ...
;     for (int it = gw; it < DEPTH * I_LAYER; it += NGW) {
;         const int l = it / I_LAYER; int r = it % I_LAYER;
; __device__ __forceinline__ void phase_rec(const P& p, unsigned char* ws, int l, LAS unsigned char* lds, int wg, int nwg) {
;     int lrank = wg, nloop = nwg, srank = wg, nstr = nwg;
;     const bool split = nwg >= 16;
;     if (split) { const int grp = wg >> 3, ngrp = (nwg + 7) >> 3, nlg = (ngrp + 1) >> 1;
;         const int full_l = nlg * 8 - ((ngrp & 1) ? (ngrp * 8 - nwg) : 0), full_s = nwg - full_l;
;         nloop = full_l; nstr = full_s; lrank = (grp >> 1) * 8 + (wg & 7); srank = (grp >> 1) * 8 + (wg & 7);
;         if (grp & 1) lrank = 1 << 30; else srank = 1 << 30; }
;     for (int rl = 0; rl < REP_LOOP; ++rl) for (int tk = lrank; tk < 128; tk += nloop) rec_loop_task(p, ws, l, lds, tk);
.LBB0_1145:
	v_readlane_b32 s0, v248, 27
	s_cmp_gt_u32 s0, 3
	s_cbranch_scc1 .Lcv_skip
	v_readlane_b32 s22, v248, 20
	s_cmpk_lg_u32 s22, 0x100
	s_cbranch_scc1 .Lcv_skip
	v_readlane_b32 s1, v248, 19
	s_bitcmp1_b32 s1, 3
	s_cbranch_scc0 .Lcv_skip
	s_waitcnt lgkmcnt(0)
	s_barrier
	v_writelane_b32 v251, s3, 0
	v_writelane_b32 v251, s4, 1
	v_writelane_b32 v251, s5, 2
	v_writelane_b32 v251, s6, 3
	v_writelane_b32 v251, s7, 4
	v_writelane_b32 v251, s8, 5
	v_writelane_b32 v251, s9, 6
	v_writelane_b32 v251, s10, 7
	v_writelane_b32 v251, s11, 8
	v_writelane_b32 v251, s12, 9
	v_writelane_b32 v251, s13, 10
	v_writelane_b32 v251, s14, 11
	v_writelane_b32 v251, s15, 12
	v_writelane_b32 v251, s16, 13
	v_writelane_b32 v251, s17, 14
	v_writelane_b32 v251, s18, 15
	v_writelane_b32 v251, s19, 16
	v_writelane_b32 v251, s20, 17
	v_writelane_b32 v251, s21, 18
	v_writelane_b32 v251, s23, 20
	v_writelane_b32 v251, s24, 21
	v_writelane_b32 v251, s25, 22
	v_writelane_b32 v251, s26, 23
	v_writelane_b32 v251, s27, 24
	v_writelane_b32 v251, s28, 25
	v_writelane_b32 v251, s29, 26
	v_writelane_b32 v251, s30, 27
	v_writelane_b32 v251, s31, 28
	v_writelane_b32 v251, s32, 29
	v_writelane_b32 v251, s33, 30
	v_writelane_b32 v251, s34, 31
	v_writelane_b32 v251, s35, 32
	v_writelane_b32 v251, s36, 33
	v_writelane_b32 v251, s37, 34
	v_writelane_b32 v251, s38, 35
	v_writelane_b32 v251, s39, 36
	v_writelane_b32 v251, s40, 37
	v_writelane_b32 v251, s41, 38
	v_writelane_b32 v251, s42, 39
	v_writelane_b32 v251, s43, 40
	v_writelane_b32 v251, s44, 41
	v_writelane_b32 v251, s45, 42
	v_writelane_b32 v251, s46, 43
	v_writelane_b32 v251, s47, 44
	v_writelane_b32 v251, s48, 45
	v_writelane_b32 v251, s49, 46
	v_writelane_b32 v251, s50, 47
	v_writelane_b32 v251, s51, 48
	v_writelane_b32 v251, s52, 49
	v_writelane_b32 v251, s53, 50
	v_writelane_b32 v251, s54, 51
	v_writelane_b32 v251, s55, 52
	v_writelane_b32 v251, s56, 53
	v_writelane_b32 v251, s57, 54
	v_writelane_b32 v251, s58, 55
	v_writelane_b32 v251, s59, 56
	v_writelane_b32 v251, s60, 57
	v_writelane_b32 v251, s61, 58
	v_writelane_b32 v251, s62, 59
	v_writelane_b32 v251, s63, 60
	v_writelane_b32 v251, s64, 61
	v_writelane_b32 v251, s65, 62
	v_writelane_b32 v251, s66, 63
	v_writelane_b32 v252, s67, 0
	v_writelane_b32 v252, s68, 1
	v_writelane_b32 v252, s69, 2
	v_writelane_b32 v252, s70, 3
	v_writelane_b32 v252, s71, 4
	v_writelane_b32 v252, s72, 5
	v_writelane_b32 v252, s73, 6
	v_writelane_b32 v252, s74, 7
	v_writelane_b32 v252, s75, 8
	v_writelane_b32 v252, s76, 9
	v_writelane_b32 v252, s77, 10
	v_writelane_b32 v252, s78, 11
	v_writelane_b32 v252, s79, 12
	v_writelane_b32 v252, s80, 13
	v_writelane_b32 v252, s81, 14
	v_writelane_b32 v252, s82, 15
	v_writelane_b32 v252, s83, 16
	v_writelane_b32 v252, s84, 17
	v_writelane_b32 v252, s85, 18
	v_writelane_b32 v252, s86, 19
	v_writelane_b32 v252, s87, 20
	v_writelane_b32 v252, s88, 21
	v_writelane_b32 v252, s89, 22
	v_writelane_b32 v252, s90, 23
	v_writelane_b32 v252, s91, 24
	v_writelane_b32 v252, s92, 25
	v_writelane_b32 v252, s93, 26
	v_writelane_b32 v252, s94, 27
	v_writelane_b32 v252, s95, 28
	v_writelane_b32 v252, s96, 29
	v_writelane_b32 v252, s97, 30
	v_writelane_b32 v252, s98, 31
	v_writelane_b32 v252, s99, 32
	v_mov_b32_e32 v253, v1
	s_lshr_b32 s22, s1, 4
	s_lshl_b32 s22, s22, 3
	s_and_b32 s1, s1, 7
	s_or_b32 s1, s22, s1
	v_writelane_b32 v250, s1, 4
	s_mul_i32 s22, s0, 0x1000
	s_add_i32 s22, s22, 0x1d300
	v_writelane_b32 v250, s22, 1
	s_add_i32 s22, s22, 0x1000
	v_writelane_b32 v250, s22, 2
	s_add_i32 s22, s22, -1
	v_writelane_b32 v250, s22, 3
	s_mov_b32 s22, 1
	v_writelane_b32 v250, s22, 0
	s_branch .Lcv_entry
